# odd mixer: conv loop rewritten (taps hoisted, flat addressing, double-buffered loads), ctx Fourier tiles moved to conv WGs, split-K consumer slab adds as rolling pre-pass
# speedup vs baseline: 1.1063x; 1.0083x over previous
.LBB0_800:
	s_andn2_b64 vcc, exec, s[2:3]
	s_cbranch_vccnz .LBB0_1227
	v_readlane_b32 s0, v254, 15
	v_readlane_b32 s1, v254, 16
	s_mov_b64 s[2:3], -1
	s_and_b64 vcc, exec, s[0:1]
	s_cbranch_vccz .LBB0_877
	v_readlane_b32 s0, v254, 1
	s_mov_b32 s73, s37
	s_mov_b32 s71, s65
	s_mov_b32 s65, s36
	s_cmpk_gt_i32 s0, 0x8f
	v_readlane_b32 s1, v254, 2
	s_cbranch_scc1 .LBB0_849
	s_cmpk_eq_i32 s5, 0x100
	v_readlane_b32 s2, v254, 1
	s_cselect_b64 s[0:1], -1, 0
	v_readlane_b32 s3, v254, 2
	s_cmpk_gt_i32 s2, 0x8f
	s_cselect_b64 s[2:3], -1, 0
	s_and_b64 s[0:1], s[2:3], s[0:1]
	s_and_b64 vcc, exec, s[0:1]
	s_cbranch_vccnz .LBB0_849
	s_waitcnt vmcnt(0)
	v_bfe_i32 v3, v200, 27, 1
	v_lshlrev_b32_e32 v0, 4, v200
	v_lshrrev_b32_e32 v3, 22, v3
	v_add_u32_e32 v3, v0, v3
	v_and_b32_e32 v3, 0xfffffc00, v3
	v_sub_u32_e32 v3, v0, v3
	v_ashrrev_i32_e32 v2, 31, v200
	v_lshrrev_b32_e32 v4, 4, v3
	v_lshrrev_b32_e32 v2, 26, v2
	v_bitop3_b32 v3, v4, v3, 32 bitop3:0x6c
	v_add_u32_e32 v2, v200, v2
	v_ashrrev_i32_e32 v5, 31, v3
	v_ashrrev_i32_e32 v2, 6, v2
	v_lshrrev_b32_e32 v5, 26, v5
	v_lshlrev_b32_e32 v4, 3, v2
	v_add_u32_e32 v5, v3, v5
	v_and_b32_e32 v4, 0x7ffffff0, v4
	v_ashrrev_i32_e32 v6, 6, v5
	v_add_u32_e32 v147, v6, v4
	v_and_b32_e32 v4, 0xc0, v5
	v_lshlrev_b32_e32 v2, 5, v2
	v_sub_u32_e32 v3, v3, v4
	v_and_b32_e32 v2, 32, v2
	v_ashrrev_i16_sdwa v3, v193, sext(v3) dst_sel:DWORD dst_unused:UNUSED_PAD src0_sel:DWORD src1_sel:BYTE_0
	v_add_u32_e32 v0, 0x2000, v0
	v_add_u32_sdwa v154, v2, sext(v3) dst_sel:DWORD dst_unused:UNUSED_PAD src0_sel:DWORD src1_sel:WORD_0
	v_ashrrev_i32_e32 v2, 31, v0
	v_lshrrev_b32_e32 v2, 22, v2
	v_add_u32_e32 v2, v0, v2
	v_ashrrev_i32_e32 v2, 10, v2
	v_mul_i32_i24_e32 v3, 0x400, v2
	s_add_u32 s4, s12, 0xfa00000
	v_sub_u32_e32 v0, v0, v3
	s_addc_u32 s8, s13, 0
	v_lshrrev_b32_e32 v3, 4, v0
	s_add_u32 s10, s12, 0xfe00000
	v_bitop3_b32 v0, v3, v0, 32 bitop3:0x6c
	s_addc_u32 s11, s13, 0
	v_ashrrev_i32_e32 v4, 31, v0
	s_add_i32 s19, s65, 0x10000
	s_add_i32 s24, s65, 0x14000
	s_add_i32 s25, s65, 0x18000
	s_add_i32 s26, s65, 0x1c000
	v_lshrrev_b32_e32 v4, 26, v4
	s_add_u32 s28, s12, 0x8800000
	s_mul_i32 s0, s73, 0x600
	v_lshlrev_b32_e32 v3, 3, v2
	v_add_u32_e32 v4, v0, v4
	s_addc_u32 s29, s13, 0
	s_ashr_i32 s1, s0, 31
	v_and_b32_e32 v3, 0x7ffffff0, v3
	v_ashrrev_i32_e32 v5, 6, v4
	s_lshl_b64 s[0:1], s[0:1], 2
	v_add_u32_e32 v155, v5, v3
	v_and_b32_e32 v3, 0xc0, v4
	s_add_u32 s0, s12, s0
	v_lshlrev_b32_e32 v2, 5, v2
	v_sub_u32_e32 v0, v0, v3
	s_addc_u32 s1, s13, s1
	v_and_b32_e32 v2, 32, v2
	v_ashrrev_i16_sdwa v0, v193, sext(v0) dst_sel:DWORD dst_unused:UNUSED_PAD src0_sel:DWORD src1_sel:BYTE_0
	s_add_u32 s30, s0, 0x16a06000
	v_add_u32_sdwa v156, v2, sext(v0) dst_sel:DWORD dst_unused:UNUSED_PAD src0_sel:DWORD src1_sel:WORD_0
	v_and_b32_e32 v157, 15, v200
	v_bfe_u32 v0, v200, 4, 2
	v_lshlrev_b32_e32 v3, 2, v200
	s_addc_u32 s36, s1, 0
	v_lshlrev_b32_e32 v158, 4, v0
	v_lshlrev_b32_e32 v2, 6, v157
	v_and_b32_e32 v3, 32, v3
	v_and_b32_e32 v160, 63, v200
	s_cmpk_lg_i32 s5, 0x100
	v_readlane_b32 s0, v254, 1
	v_bitop3_b32 v159, v158, v3, v2 bitop3:0x36
	v_lshlrev_b32_e32 v146, 2, v0
	v_cmp_eq_u32_e64 s[40:41], 0, v160
	s_cselect_b32 s37, s5, 0x100
	s_mov_b32 s38, s0
	v_readlane_b32 s1, v254, 2
	s_branch .LBB0_806

.LBB0_826:
	s_lshr_b64 s[0:1], s[2:3], 14
	s_and_b32 s0, s0, 0xfc0000
	s_add_u32 s0, s28, s0
	s_addc_u32 s1, s29, 0
	v_lshl_add_u64 v[150:151], s[0:1], 0, v[148:149]
	s_andn2_b64 vcc, exec, s[42:43]
	s_cbranch_vccnz .Lfo_noadd
	v_mov_b64_e32 v[152:153], v[150:151]
	s_mov_b64 s[0:1], 0x2000
	global_load_dwordx4 v[138:141], v[152:153], off
	v_lshl_add_u64 v[152:153], v[152:153], 0, s[0:1]
	global_load_dwordx4 v[142:145], v[152:153], off
	v_lshl_add_u64 v[152:153], v[152:153], 0, s[0:1]
	global_load_dwordx4 v[168:171], v[152:153], off
	v_lshl_add_u64 v[152:153], v[152:153], 0, s[0:1]
	global_load_dwordx4 v[172:175], v[152:153], off
	v_lshl_add_u64 v[152:153], v[152:153], 0, s[0:1]
	global_load_dwordx4 v[176:179], v[152:153], off
	v_lshl_add_u64 v[152:153], v[152:153], 0, s[0:1]
	global_load_dwordx4 v[180:183], v[152:153], off
	v_lshl_add_u64 v[152:153], v[152:153], 0, s[0:1]
	global_load_dwordx4 v[184:187], v[152:153], off
	v_lshl_add_u64 v[152:153], v[152:153], 0, s[0:1]
	global_load_dwordx4 v[202:205], v[152:153], off
	v_lshl_add_u64 v[152:153], v[152:153], 0, s[0:1]
	global_load_dwordx4 v[206:209], v[152:153], off
	v_lshl_add_u64 v[152:153], v[152:153], 0, s[0:1]
	global_load_dwordx4 v[210:213], v[152:153], off
	v_lshl_add_u64 v[152:153], v[152:153], 0, s[0:1]
	global_load_dwordx4 v[214:217], v[152:153], off
	v_lshl_add_u64 v[152:153], v[152:153], 0, s[0:1]
	global_load_dwordx4 v[218:221], v[152:153], off
	v_lshl_add_u64 v[152:153], v[152:153], 0, s[0:1]
	global_load_dwordx4 v[242:245], v[152:153], off
	v_lshl_add_u64 v[152:153], v[152:153], 0, s[0:1]
	global_load_dwordx4 v[246:249], v[152:153], off
	v_lshl_add_u64 v[152:153], v[152:153], 0, s[0:1]
	global_load_dwordx4 v[194:197], v[152:153], off
	v_lshl_add_u64 v[152:153], v[152:153], 0, s[0:1]
	global_load_dwordx4 v[164:167], v[152:153], off
	v_lshl_add_u64 v[152:153], v[152:153], 0, s[0:1]
	s_waitcnt vmcnt(15)
	v_add_f32_e32 v126, v126, v138
	v_add_f32_e32 v127, v127, v139
	v_add_f32_e32 v128, v128, v140
	v_add_f32_e32 v129, v129, v141
	global_load_dwordx4 v[138:141], v[152:153], off
	v_lshl_add_u64 v[152:153], v[152:153], 0, s[0:1]
	s_waitcnt vmcnt(15)
	v_add_f32_e32 v122, v122, v142
	v_add_f32_e32 v123, v123, v143
	v_add_f32_e32 v124, v124, v144
	v_add_f32_e32 v125, v125, v145
	global_load_dwordx4 v[142:145], v[152:153], off
	v_lshl_add_u64 v[152:153], v[152:153], 0, s[0:1]
	s_waitcnt vmcnt(15)
	v_add_f32_e32 v118, v118, v168
	v_add_f32_e32 v119, v119, v169
	v_add_f32_e32 v120, v120, v170
	v_add_f32_e32 v121, v121, v171
	global_load_dwordx4 v[168:171], v[152:153], off
	v_lshl_add_u64 v[152:153], v[152:153], 0, s[0:1]
	s_waitcnt vmcnt(15)
	v_add_f32_e32 v114, v114, v172
	v_add_f32_e32 v115, v115, v173
	v_add_f32_e32 v116, v116, v174
	v_add_f32_e32 v117, v117, v175
	global_load_dwordx4 v[172:175], v[152:153], off
	v_lshl_add_u64 v[152:153], v[152:153], 0, s[0:1]
	s_waitcnt vmcnt(15)
	v_add_f32_e32 v110, v110, v176
	v_add_f32_e32 v111, v111, v177
	v_add_f32_e32 v112, v112, v178
	v_add_f32_e32 v113, v113, v179
	global_load_dwordx4 v[176:179], v[152:153], off
	v_lshl_add_u64 v[152:153], v[152:153], 0, s[0:1]
	s_waitcnt vmcnt(15)
	v_add_f32_e32 v106, v106, v180
	v_add_f32_e32 v107, v107, v181
	v_add_f32_e32 v108, v108, v182
	v_add_f32_e32 v109, v109, v183
	global_load_dwordx4 v[180:183], v[152:153], off
	v_lshl_add_u64 v[152:153], v[152:153], 0, s[0:1]
	s_waitcnt vmcnt(15)
	v_add_f32_e32 v102, v102, v184
	v_add_f32_e32 v103, v103, v185
	v_add_f32_e32 v104, v104, v186
	v_add_f32_e32 v105, v105, v187
	global_load_dwordx4 v[184:187], v[152:153], off
	v_lshl_add_u64 v[152:153], v[152:153], 0, s[0:1]
	s_waitcnt vmcnt(15)
	v_add_f32_e32 v98, v98, v202
	v_add_f32_e32 v99, v99, v203
	v_add_f32_e32 v100, v100, v204
	v_add_f32_e32 v101, v101, v205
	global_load_dwordx4 v[202:205], v[152:153], off
	v_lshl_add_u64 v[152:153], v[152:153], 0, s[0:1]
	s_waitcnt vmcnt(15)
	v_add_f32_e32 v94, v94, v206
	v_add_f32_e32 v95, v95, v207
	v_add_f32_e32 v96, v96, v208
	v_add_f32_e32 v97, v97, v209
	global_load_dwordx4 v[206:209], v[152:153], off
	v_lshl_add_u64 v[152:153], v[152:153], 0, s[0:1]
	s_waitcnt vmcnt(15)
	v_add_f32_e32 v90, v90, v210
	v_add_f32_e32 v91, v91, v211
	v_add_f32_e32 v92, v92, v212
	v_add_f32_e32 v93, v93, v213
	global_load_dwordx4 v[210:213], v[152:153], off
	v_lshl_add_u64 v[152:153], v[152:153], 0, s[0:1]
	s_waitcnt vmcnt(15)
	v_add_f32_e32 v86, v86, v214
	v_add_f32_e32 v87, v87, v215
	v_add_f32_e32 v88, v88, v216
	v_add_f32_e32 v89, v89, v217
	global_load_dwordx4 v[214:217], v[152:153], off
	v_lshl_add_u64 v[152:153], v[152:153], 0, s[0:1]
	s_waitcnt vmcnt(15)
	v_add_f32_e32 v82, v82, v218
	v_add_f32_e32 v83, v83, v219
	v_add_f32_e32 v84, v84, v220
	v_add_f32_e32 v85, v85, v221
	global_load_dwordx4 v[218:221], v[152:153], off
	v_lshl_add_u64 v[152:153], v[152:153], 0, s[0:1]
	s_waitcnt vmcnt(15)
	v_add_f32_e32 v78, v78, v242
	v_add_f32_e32 v79, v79, v243
	v_add_f32_e32 v80, v80, v244
	v_add_f32_e32 v81, v81, v245
	global_load_dwordx4 v[242:245], v[152:153], off
	v_lshl_add_u64 v[152:153], v[152:153], 0, s[0:1]
	s_waitcnt vmcnt(15)
	v_add_f32_e32 v74, v74, v246
	v_add_f32_e32 v75, v75, v247
	v_add_f32_e32 v76, v76, v248
	v_add_f32_e32 v77, v77, v249
	global_load_dwordx4 v[246:249], v[152:153], off
	v_lshl_add_u64 v[152:153], v[152:153], 0, s[0:1]
	s_waitcnt vmcnt(15)
	v_add_f32_e32 v70, v70, v194
	v_add_f32_e32 v71, v71, v195
	v_add_f32_e32 v72, v72, v196
	v_add_f32_e32 v73, v73, v197
	global_load_dwordx4 v[194:197], v[152:153], off
	v_lshl_add_u64 v[152:153], v[152:153], 0, s[0:1]
	s_waitcnt vmcnt(15)
	v_add_f32_e32 v66, v66, v164
	v_add_f32_e32 v67, v67, v165
	v_add_f32_e32 v68, v68, v166
	v_add_f32_e32 v69, v69, v167
	global_load_dwordx4 v[164:167], v[152:153], off
	s_waitcnt vmcnt(15)
	v_add_f32_e32 v62, v62, v138
	v_add_f32_e32 v63, v63, v139
	v_add_f32_e32 v64, v64, v140
	v_add_f32_e32 v65, v65, v141
	s_waitcnt vmcnt(14)
	v_add_f32_e32 v58, v58, v142
	v_add_f32_e32 v59, v59, v143
	v_add_f32_e32 v60, v60, v144
	v_add_f32_e32 v61, v61, v145
	s_waitcnt vmcnt(13)
	v_add_f32_e32 v54, v54, v168
	v_add_f32_e32 v55, v55, v169
	v_add_f32_e32 v56, v56, v170
	v_add_f32_e32 v57, v57, v171
	s_waitcnt vmcnt(12)
	v_add_f32_e32 v50, v50, v172
	v_add_f32_e32 v51, v51, v173
	v_add_f32_e32 v52, v52, v174
	v_add_f32_e32 v53, v53, v175
	s_waitcnt vmcnt(11)
	v_add_f32_e32 v46, v46, v176
	v_add_f32_e32 v47, v47, v177
	v_add_f32_e32 v48, v48, v178
	v_add_f32_e32 v49, v49, v179
	s_waitcnt vmcnt(10)
	v_add_f32_e32 v42, v42, v180
	v_add_f32_e32 v43, v43, v181
	v_add_f32_e32 v44, v44, v182
	v_add_f32_e32 v45, v45, v183
	s_waitcnt vmcnt(9)
	v_add_f32_e32 v38, v38, v184
	v_add_f32_e32 v39, v39, v185
	v_add_f32_e32 v40, v40, v186
	v_add_f32_e32 v41, v41, v187
	s_waitcnt vmcnt(8)
	v_add_f32_e32 v34, v34, v202
	v_add_f32_e32 v35, v35, v203
	v_add_f32_e32 v36, v36, v204
	v_add_f32_e32 v37, v37, v205
	s_waitcnt vmcnt(7)
	v_add_f32_e32 v30, v30, v206
	v_add_f32_e32 v31, v31, v207
	v_add_f32_e32 v32, v32, v208
	v_add_f32_e32 v33, v33, v209
	s_waitcnt vmcnt(6)
	v_add_f32_e32 v26, v26, v210
	v_add_f32_e32 v27, v27, v211
	v_add_f32_e32 v28, v28, v212
	v_add_f32_e32 v29, v29, v213
	s_waitcnt vmcnt(5)
	v_add_f32_e32 v22, v22, v214
	v_add_f32_e32 v23, v23, v215
	v_add_f32_e32 v24, v24, v216
	v_add_f32_e32 v25, v25, v217
	s_waitcnt vmcnt(4)
	v_add_f32_e32 v18, v18, v218
	v_add_f32_e32 v19, v19, v219
	v_add_f32_e32 v20, v20, v220
	v_add_f32_e32 v21, v21, v221
	s_waitcnt vmcnt(3)
	v_add_f32_e32 v14, v14, v242
	v_add_f32_e32 v15, v15, v243
	v_add_f32_e32 v16, v16, v244
	v_add_f32_e32 v17, v17, v245
	s_waitcnt vmcnt(2)
	v_add_f32_e32 v10, v10, v246
	v_add_f32_e32 v11, v11, v247
	v_add_f32_e32 v12, v12, v248
	v_add_f32_e32 v13, v13, v249
	s_waitcnt vmcnt(1)
	v_add_f32_e32 v6, v6, v194
	v_add_f32_e32 v7, v7, v195
	v_add_f32_e32 v8, v8, v196
	v_add_f32_e32 v9, v9, v197
	s_waitcnt vmcnt(0)
	v_add_f32_e32 v2, v2, v164
	v_add_f32_e32 v3, v3, v165
	v_add_f32_e32 v4, v4, v166
	v_add_f32_e32 v5, v5, v167
	s_mov_b64 s[42:43], 0
.Lfo_noadd:
	v_cndmask_b32_e64 v0, 0, 1, s[42:43]
	v_cmp_ne_u32_e64 s[44:45], 1, v0
	s_andn2_b64 vcc, exec, s[42:43]
	s_branch .LBB0_828
	v_add_co_u32_e32 v134, vcc, 0x2000, v150
	s_nop 1
	v_addc_co_u32_e32 v135, vcc, 0, v151, vcc
	v_add_co_u32_e32 v138, vcc, 0x10000, v150
	global_load_dwordx4 v[130:133], v[150:151], off
	s_nop 0
	global_load_dwordx4 v[134:137], v[134:135], off
	v_addc_co_u32_e32 v139, vcc, 0, v151, vcc
	v_add_co_u32_e32 v142, vcc, 0x12000, v150
	s_nop 1
	v_addc_co_u32_e32 v143, vcc, 0, v151, vcc
	global_load_dwordx4 v[138:141], v[138:139], off
	s_nop 0
	global_load_dwordx4 v[142:145], v[142:143], off
.LBB0_828:
	s_lshl_b32 s2, s48, 8
	v_add_u32_e32 v152, s2, v161
	v_ashrrev_i32_e32 v153, 31, v152
	v_lshlrev_b64 v[162:163], 11, v[152:153]
	v_lshl_add_u64 v[162:163], s[6:7], 0, v[162:163]
	s_lshl_b32 s86, s47, 6
	v_add_f32_e32 v164, v128, v132
	v_add_f32_e32 v165, v129, v133
	v_add_f32_e32 v166, v126, v130
	v_add_f32_e32 v167, v127, v131
	v_lshl_add_u64 v[162:163], v[162:163], 0, s[86:87]
	v_lshlrev_b32_e32 v0, 1, v146
	v_cndmask_b32_e64 v153, v129, v165, s[42:43]
	v_cndmask_b32_e64 v165, v128, v164, s[42:43]
	v_cndmask_b32_e64 v164, v127, v167, s[42:43]
	v_cndmask_b32_e64 v166, v126, v166, s[42:43]
	v_lshl_add_u64 v[162:163], v[162:163], 0, v[0:1]
	v_cvt_pk_bf16_f32 v164, v166, v164
	v_cvt_pk_bf16_f32 v165, v165, v153
	global_store_dwordx2 v[162:163], v[164:165], off
	v_add_f32_e32 v164, v124, v136
	v_add_f32_e32 v165, v125, v137
	v_add_f32_e32 v166, v122, v134
	v_add_f32_e32 v167, v123, v135
	v_cndmask_b32_e64 v153, v125, v165, s[42:43]
	v_cndmask_b32_e64 v165, v124, v164, s[42:43]
	v_cndmask_b32_e64 v164, v123, v167, s[42:43]
	v_cndmask_b32_e64 v166, v122, v166, s[42:43]
	v_cvt_pk_bf16_f32 v164, v166, v164
	v_cvt_pk_bf16_f32 v165, v165, v153
	global_store_dwordx2 v[162:163], v[164:165], off offset:32
	v_add_f32_e32 v164, v96, v140
	v_add_f32_e32 v165, v97, v141
	v_add_f32_e32 v166, v94, v138
	v_add_f32_e32 v167, v95, v139
	v_cndmask_b32_e64 v153, v97, v165, s[42:43]
	v_cndmask_b32_e64 v165, v96, v164, s[42:43]
	v_cndmask_b32_e64 v164, v95, v167, s[42:43]
	v_cndmask_b32_e64 v166, v94, v166, s[42:43]
	v_cvt_pk_bf16_f32 v164, v166, v164
	v_cvt_pk_bf16_f32 v165, v165, v153
	global_store_dwordx2 v[162:163], v[164:165], off offset:256
	v_add_f32_e32 v164, v92, v144
	v_add_f32_e32 v165, v93, v145
	v_add_f32_e32 v166, v90, v142
	v_add_f32_e32 v167, v91, v143
	v_cndmask_b32_e64 v153, v93, v165, s[42:43]
	v_cndmask_b32_e64 v165, v92, v164, s[42:43]
	v_cndmask_b32_e64 v164, v91, v167, s[42:43]
	v_cndmask_b32_e64 v166, v90, v166, s[42:43]
	v_cvt_pk_bf16_f32 v164, v166, v164
	v_cvt_pk_bf16_f32 v165, v165, v153
	s_and_b64 vcc, exec, s[44:45]
	global_store_dwordx2 v[162:163], v[164:165], off offset:288
	s_branch .LBB0_830
	v_add_co_u32_e32 v130, vcc, 0x4000, v150
	s_nop 1
	v_addc_co_u32_e32 v131, vcc, 0, v151, vcc
	v_add_co_u32_e32 v134, vcc, 0x6000, v150
	s_nop 1
	v_addc_co_u32_e32 v135, vcc, 0, v151, vcc
	v_add_co_u32_e32 v138, vcc, 0x14000, v150
	global_load_dwordx4 v[130:133], v[130:131], off
	s_nop 0
	global_load_dwordx4 v[134:137], v[134:135], off
	v_addc_co_u32_e32 v139, vcc, 0, v151, vcc
	v_add_co_u32_e32 v142, vcc, 0x16000, v150
	s_nop 1
	v_addc_co_u32_e32 v143, vcc, 0, v151, vcc
	global_load_dwordx4 v[138:141], v[138:139], off
	s_nop 0
	global_load_dwordx4 v[142:145], v[142:143], off
.LBB0_830:
	v_add3_u32 v162, v161, s2, 16
	v_ashrrev_i32_e32 v163, 31, v162
	s_lshl_b32 s0, s47, 5
	v_lshlrev_b64 v[162:163], 11, v[162:163]
	v_lshl_add_u64 v[162:163], s[6:7], 0, v[162:163]
	s_lshl_b32 s86, s0, 1
	v_add_f32_e32 v164, v120, v132
	v_add_f32_e32 v165, v121, v133
	v_add_f32_e32 v166, v118, v130
	v_add_f32_e32 v167, v119, v131
	v_lshl_add_u64 v[162:163], v[162:163], 0, s[86:87]
	v_cndmask_b32_e64 v153, v121, v165, s[42:43]
	v_cndmask_b32_e64 v165, v120, v164, s[42:43]
	v_cndmask_b32_e64 v164, v119, v167, s[42:43]
	v_cndmask_b32_e64 v166, v118, v166, s[42:43]
	v_lshl_add_u64 v[162:163], v[162:163], 0, v[0:1]
	v_cvt_pk_bf16_f32 v164, v166, v164
	v_cvt_pk_bf16_f32 v165, v165, v153
	global_store_dwordx2 v[162:163], v[164:165], off
	v_add_f32_e32 v164, v116, v136
	v_add_f32_e32 v165, v117, v137
	v_add_f32_e32 v166, v114, v134
	v_add_f32_e32 v167, v115, v135
	v_cndmask_b32_e64 v153, v117, v165, s[42:43]
	v_cndmask_b32_e64 v165, v116, v164, s[42:43]
	v_cndmask_b32_e64 v164, v115, v167, s[42:43]
	v_cndmask_b32_e64 v166, v114, v166, s[42:43]
	v_cvt_pk_bf16_f32 v164, v166, v164
	v_cvt_pk_bf16_f32 v165, v165, v153
	global_store_dwordx2 v[162:163], v[164:165], off offset:32
	v_add_f32_e32 v164, v88, v140
	v_add_f32_e32 v165, v89, v141
	v_add_f32_e32 v166, v86, v138
	v_add_f32_e32 v167, v87, v139
	v_cndmask_b32_e64 v153, v89, v165, s[42:43]
	v_cndmask_b32_e64 v165, v88, v164, s[42:43]
	v_cndmask_b32_e64 v164, v87, v167, s[42:43]
	v_cndmask_b32_e64 v166, v86, v166, s[42:43]
	v_cvt_pk_bf16_f32 v164, v166, v164
	v_cvt_pk_bf16_f32 v165, v165, v153
	global_store_dwordx2 v[162:163], v[164:165], off offset:256
	v_add_f32_e32 v164, v84, v144
	v_add_f32_e32 v165, v85, v145
	v_add_f32_e32 v166, v82, v142
	v_add_f32_e32 v167, v83, v143
	v_cndmask_b32_e64 v153, v85, v165, s[42:43]
	v_cndmask_b32_e64 v165, v84, v164, s[42:43]
	v_cndmask_b32_e64 v164, v83, v167, s[42:43]
	v_cndmask_b32_e64 v166, v82, v166, s[42:43]
	v_cvt_pk_bf16_f32 v164, v166, v164
	v_cvt_pk_bf16_f32 v165, v165, v153
	s_and_b64 vcc, exec, s[44:45]
	global_store_dwordx2 v[162:163], v[164:165], off offset:288
	s_branch .LBB0_832
	v_add_co_u32_e32 v130, vcc, 0x8000, v150
	s_nop 1
	v_addc_co_u32_e32 v131, vcc, 0, v151, vcc
	v_add_co_u32_e32 v134, vcc, 0xa000, v150
	s_nop 1
	v_addc_co_u32_e32 v135, vcc, 0, v151, vcc
	v_add_co_u32_e32 v138, vcc, 0x18000, v150
	global_load_dwordx4 v[130:133], v[130:131], off
	s_nop 0
	global_load_dwordx4 v[134:137], v[134:135], off
	v_addc_co_u32_e32 v139, vcc, 0, v151, vcc
	v_add_co_u32_e32 v142, vcc, 0x1a000, v150
	s_nop 1
	v_addc_co_u32_e32 v143, vcc, 0, v151, vcc
	global_load_dwordx4 v[138:141], v[138:139], off
	s_nop 0
	global_load_dwordx4 v[142:145], v[142:143], off
.LBB0_832:
	v_add3_u32 v162, v161, s2, 32
	v_ashrrev_i32_e32 v163, 31, v162
	v_lshlrev_b64 v[162:163], 11, v[162:163]
	v_lshl_add_u64 v[162:163], s[6:7], 0, v[162:163]
	v_add_f32_e32 v164, v112, v132
	v_add_f32_e32 v165, v113, v133
	v_add_f32_e32 v166, v110, v130
	v_add_f32_e32 v167, v111, v131
	v_lshl_add_u64 v[162:163], v[162:163], 0, s[86:87]
	v_cndmask_b32_e64 v153, v113, v165, s[42:43]
	v_cndmask_b32_e64 v165, v112, v164, s[42:43]
	v_cndmask_b32_e64 v164, v111, v167, s[42:43]
	v_cndmask_b32_e64 v166, v110, v166, s[42:43]
	v_lshl_add_u64 v[162:163], v[162:163], 0, v[0:1]
	v_cvt_pk_bf16_f32 v164, v166, v164
	v_cvt_pk_bf16_f32 v165, v165, v153
	global_store_dwordx2 v[162:163], v[164:165], off
	v_add_f32_e32 v164, v108, v136
	v_add_f32_e32 v165, v109, v137
	v_add_f32_e32 v166, v106, v134
	v_add_f32_e32 v167, v107, v135
	v_cndmask_b32_e64 v153, v109, v165, s[42:43]
	v_cndmask_b32_e64 v165, v108, v164, s[42:43]
	v_cndmask_b32_e64 v164, v107, v167, s[42:43]
	v_cndmask_b32_e64 v166, v106, v166, s[42:43]
	v_cvt_pk_bf16_f32 v164, v166, v164
	v_cvt_pk_bf16_f32 v165, v165, v153
	global_store_dwordx2 v[162:163], v[164:165], off offset:32
	v_add_f32_e32 v164, v80, v140
	v_add_f32_e32 v165, v81, v141
	v_add_f32_e32 v166, v78, v138
	v_add_f32_e32 v167, v79, v139
	v_cndmask_b32_e64 v153, v81, v165, s[42:43]
	v_cndmask_b32_e64 v165, v80, v164, s[42:43]
	v_cndmask_b32_e64 v164, v79, v167, s[42:43]
	v_cndmask_b32_e64 v166, v78, v166, s[42:43]
	v_cvt_pk_bf16_f32 v164, v166, v164
	v_cvt_pk_bf16_f32 v165, v165, v153
	global_store_dwordx2 v[162:163], v[164:165], off offset:256
	v_add_f32_e32 v164, v76, v144
	v_add_f32_e32 v165, v77, v145
	v_add_f32_e32 v166, v74, v142
	v_add_f32_e32 v167, v75, v143
	v_cndmask_b32_e64 v153, v77, v165, s[42:43]
	v_cndmask_b32_e64 v165, v76, v164, s[42:43]
	v_cndmask_b32_e64 v164, v75, v167, s[42:43]
	v_cndmask_b32_e64 v166, v74, v166, s[42:43]
	v_cvt_pk_bf16_f32 v164, v166, v164
	v_cvt_pk_bf16_f32 v165, v165, v153
	s_and_b64 vcc, exec, s[44:45]
	global_store_dwordx2 v[162:163], v[164:165], off offset:288
	s_branch .LBB0_834
	v_add_co_u32_e32 v130, vcc, 0xc000, v150
	s_nop 1
	v_addc_co_u32_e32 v131, vcc, 0, v151, vcc
	v_add_co_u32_e32 v134, vcc, 0xe000, v150
	s_nop 1
	v_addc_co_u32_e32 v135, vcc, 0, v151, vcc
	v_add_co_u32_e32 v138, vcc, 0x1c000, v150
	global_load_dwordx4 v[130:133], v[130:131], off
	s_nop 0
	global_load_dwordx4 v[134:137], v[134:135], off
	v_addc_co_u32_e32 v139, vcc, 0, v151, vcc
	v_add_co_u32_e32 v142, vcc, 0x1e000, v150
	s_nop 1
	v_addc_co_u32_e32 v143, vcc, 0, v151, vcc
	global_load_dwordx4 v[138:141], v[138:139], off
	s_nop 0
	global_load_dwordx4 v[142:145], v[142:143], off
.LBB0_834:
	v_add3_u32 v162, v161, s2, 48
	v_ashrrev_i32_e32 v163, 31, v162
	v_lshlrev_b64 v[162:163], 11, v[162:163]
	v_lshl_add_u64 v[162:163], s[6:7], 0, v[162:163]
	v_add_f32_e32 v164, v104, v132
	v_add_f32_e32 v165, v105, v133
	v_add_f32_e32 v166, v102, v130
	v_add_f32_e32 v167, v103, v131
	v_lshl_add_u64 v[162:163], v[162:163], 0, s[86:87]
	v_cndmask_b32_e64 v153, v105, v165, s[42:43]
	v_cndmask_b32_e64 v161, v104, v164, s[42:43]
	v_cndmask_b32_e64 v164, v103, v167, s[42:43]
	v_cndmask_b32_e64 v165, v102, v166, s[42:43]
	v_lshl_add_u64 v[162:163], v[162:163], 0, v[0:1]
	v_cvt_pk_bf16_f32 v164, v165, v164
	v_cvt_pk_bf16_f32 v165, v161, v153
	global_store_dwordx2 v[162:163], v[164:165], off
	v_add_f32_e32 v164, v100, v136
	v_add_f32_e32 v165, v101, v137
	v_add_f32_e32 v166, v98, v134
	v_add_f32_e32 v167, v99, v135
	v_cndmask_b32_e64 v153, v101, v165, s[42:43]
	v_cndmask_b32_e64 v161, v100, v164, s[42:43]
	v_cndmask_b32_e64 v164, v99, v167, s[42:43]
	v_cndmask_b32_e64 v165, v98, v166, s[42:43]
	v_cvt_pk_bf16_f32 v164, v165, v164
	v_cvt_pk_bf16_f32 v165, v161, v153
	global_store_dwordx2 v[162:163], v[164:165], off offset:32
	v_add_f32_e32 v164, v72, v140
	v_add_f32_e32 v165, v73, v141
	v_add_f32_e32 v166, v70, v138
	v_add_f32_e32 v167, v71, v139
	v_cndmask_b32_e64 v153, v73, v165, s[42:43]
	v_cndmask_b32_e64 v161, v72, v164, s[42:43]
	v_cndmask_b32_e64 v164, v71, v167, s[42:43]
	v_cndmask_b32_e64 v165, v70, v166, s[42:43]
	v_cvt_pk_bf16_f32 v164, v165, v164
	v_cvt_pk_bf16_f32 v165, v161, v153
	global_store_dwordx2 v[162:163], v[164:165], off offset:256
	v_add_f32_e32 v164, v68, v144
	v_add_f32_e32 v165, v69, v145
	v_add_f32_e32 v166, v66, v142
	v_add_f32_e32 v167, v67, v143
	v_cndmask_b32_e64 v153, v69, v165, s[42:43]
	v_cndmask_b32_e64 v161, v68, v164, s[42:43]
	v_cndmask_b32_e64 v164, v67, v167, s[42:43]
	v_cndmask_b32_e64 v165, v66, v166, s[42:43]
	v_cvt_pk_bf16_f32 v164, v165, v164
	v_cvt_pk_bf16_f32 v165, v161, v153
	s_and_b64 vcc, exec, s[44:45]
	global_store_dwordx2 v[162:163], v[164:165], off offset:288
	s_branch .LBB0_836
	v_add_co_u32_e32 v130, vcc, 0x20000, v150
	s_nop 1
	v_addc_co_u32_e32 v131, vcc, 0, v151, vcc
	v_add_co_u32_e32 v134, vcc, 0x22000, v150
	s_nop 1
	v_addc_co_u32_e32 v135, vcc, 0, v151, vcc
	v_add_co_u32_e32 v138, vcc, 0x30000, v150
	global_load_dwordx4 v[130:133], v[130:131], off
	s_nop 0
	global_load_dwordx4 v[134:137], v[134:135], off
	v_addc_co_u32_e32 v139, vcc, 0, v151, vcc
	v_add_co_u32_e32 v142, vcc, 0x32000, v150
	s_nop 1
	v_addc_co_u32_e32 v143, vcc, 0, v151, vcc
	global_load_dwordx4 v[138:141], v[138:139], off
	s_nop 0
	global_load_dwordx4 v[142:145], v[142:143], off
.LBB0_836:
	v_add_u32_e32 v162, 0x80, v152
	v_ashrrev_i32_e32 v163, 31, v162
	v_lshlrev_b64 v[162:163], 11, v[162:163]
	v_lshl_add_u64 v[162:163], s[6:7], 0, v[162:163]
	v_add_f32_e32 v164, v64, v132
	v_add_f32_e32 v165, v65, v133
	v_add_f32_e32 v166, v62, v130
	v_add_f32_e32 v167, v63, v131
	v_lshl_add_u64 v[162:163], v[162:163], 0, s[86:87]
	v_cndmask_b32_e64 v153, v65, v165, s[42:43]
	v_cndmask_b32_e64 v161, v64, v164, s[42:43]
	v_cndmask_b32_e64 v164, v63, v167, s[42:43]
	v_cndmask_b32_e64 v165, v62, v166, s[42:43]
	v_lshl_add_u64 v[162:163], v[162:163], 0, v[0:1]
	v_cvt_pk_bf16_f32 v164, v165, v164
	v_cvt_pk_bf16_f32 v165, v161, v153
	global_store_dwordx2 v[162:163], v[164:165], off
	v_add_f32_e32 v164, v60, v136
	v_add_f32_e32 v165, v61, v137
	v_add_f32_e32 v166, v58, v134
	v_add_f32_e32 v167, v59, v135
	v_cndmask_b32_e64 v153, v61, v165, s[42:43]
	v_cndmask_b32_e64 v161, v60, v164, s[42:43]
	v_cndmask_b32_e64 v164, v59, v167, s[42:43]
	v_cndmask_b32_e64 v165, v58, v166, s[42:43]
	v_cvt_pk_bf16_f32 v164, v165, v164
	v_cvt_pk_bf16_f32 v165, v161, v153
	global_store_dwordx2 v[162:163], v[164:165], off offset:32
	v_add_f32_e32 v164, v32, v140
	v_add_f32_e32 v165, v33, v141
	v_add_f32_e32 v166, v30, v138
	v_add_f32_e32 v167, v31, v139
	v_cndmask_b32_e64 v153, v33, v165, s[42:43]
	v_cndmask_b32_e64 v161, v32, v164, s[42:43]
	v_cndmask_b32_e64 v164, v31, v167, s[42:43]
	v_cndmask_b32_e64 v165, v30, v166, s[42:43]
	v_cvt_pk_bf16_f32 v164, v165, v164
	v_cvt_pk_bf16_f32 v165, v161, v153
	global_store_dwordx2 v[162:163], v[164:165], off offset:256
	v_add_f32_e32 v164, v28, v144
	v_add_f32_e32 v165, v29, v145
	v_add_f32_e32 v166, v26, v142
	v_add_f32_e32 v167, v27, v143
	v_cndmask_b32_e64 v153, v29, v165, s[42:43]
	v_cndmask_b32_e64 v161, v28, v164, s[42:43]
	v_cndmask_b32_e64 v164, v27, v167, s[42:43]
	v_cndmask_b32_e64 v165, v26, v166, s[42:43]
	v_cvt_pk_bf16_f32 v164, v165, v164
	v_cvt_pk_bf16_f32 v165, v161, v153
	s_and_b64 vcc, exec, s[44:45]
	global_store_dwordx2 v[162:163], v[164:165], off offset:288
	s_branch .LBB0_838
	v_add_co_u32_e32 v130, vcc, 0x24000, v150
	s_nop 1
	v_addc_co_u32_e32 v131, vcc, 0, v151, vcc
	v_add_co_u32_e32 v134, vcc, 0x26000, v150
	s_nop 1
	v_addc_co_u32_e32 v135, vcc, 0, v151, vcc
	v_add_co_u32_e32 v138, vcc, 0x34000, v150
	global_load_dwordx4 v[130:133], v[130:131], off
	s_nop 0
	global_load_dwordx4 v[134:137], v[134:135], off
	v_addc_co_u32_e32 v139, vcc, 0, v151, vcc
	v_add_co_u32_e32 v142, vcc, 0x36000, v150
	s_nop 1
	v_addc_co_u32_e32 v143, vcc, 0, v151, vcc
	global_load_dwordx4 v[138:141], v[138:139], off
	s_nop 0
	global_load_dwordx4 v[142:145], v[142:143], off
.LBB0_838:
	v_add_u32_e32 v162, 0x90, v152
	v_ashrrev_i32_e32 v163, 31, v162
	v_lshlrev_b64 v[162:163], 11, v[162:163]
	v_lshl_add_u64 v[162:163], s[6:7], 0, v[162:163]
	v_add_f32_e32 v164, v56, v132
	v_add_f32_e32 v165, v57, v133
	v_add_f32_e32 v166, v54, v130
	v_add_f32_e32 v167, v55, v131
	v_lshl_add_u64 v[162:163], v[162:163], 0, s[86:87]
	v_cndmask_b32_e64 v153, v57, v165, s[42:43]
	v_cndmask_b32_e64 v161, v56, v164, s[42:43]
	v_cndmask_b32_e64 v164, v55, v167, s[42:43]
	v_cndmask_b32_e64 v165, v54, v166, s[42:43]
	v_lshl_add_u64 v[162:163], v[162:163], 0, v[0:1]
	v_cvt_pk_bf16_f32 v164, v165, v164
	v_cvt_pk_bf16_f32 v165, v161, v153
	global_store_dwordx2 v[162:163], v[164:165], off
	v_add_f32_e32 v164, v52, v136
	v_add_f32_e32 v165, v53, v137
	v_add_f32_e32 v166, v50, v134
	v_add_f32_e32 v167, v51, v135
	v_cndmask_b32_e64 v153, v53, v165, s[42:43]
	v_cndmask_b32_e64 v161, v52, v164, s[42:43]
	v_cndmask_b32_e64 v164, v51, v167, s[42:43]
	v_cndmask_b32_e64 v165, v50, v166, s[42:43]
	v_cvt_pk_bf16_f32 v164, v165, v164
	v_cvt_pk_bf16_f32 v165, v161, v153
	global_store_dwordx2 v[162:163], v[164:165], off offset:32
	v_add_f32_e32 v164, v24, v140
	v_add_f32_e32 v165, v25, v141
	v_add_f32_e32 v166, v22, v138
	v_add_f32_e32 v167, v23, v139
	v_cndmask_b32_e64 v153, v25, v165, s[42:43]
	v_cndmask_b32_e64 v161, v24, v164, s[42:43]
	v_cndmask_b32_e64 v164, v23, v167, s[42:43]
	v_cndmask_b32_e64 v165, v22, v166, s[42:43]
	v_cvt_pk_bf16_f32 v164, v165, v164
	v_cvt_pk_bf16_f32 v165, v161, v153
	global_store_dwordx2 v[162:163], v[164:165], off offset:256
	v_add_f32_e32 v164, v20, v144
	v_add_f32_e32 v165, v21, v145
	v_add_f32_e32 v166, v18, v142
	v_add_f32_e32 v167, v19, v143
	v_cndmask_b32_e64 v153, v21, v165, s[42:43]
	v_cndmask_b32_e64 v161, v20, v164, s[42:43]
	v_cndmask_b32_e64 v164, v19, v167, s[42:43]
	v_cndmask_b32_e64 v165, v18, v166, s[42:43]
	v_cvt_pk_bf16_f32 v164, v165, v164
	v_cvt_pk_bf16_f32 v165, v161, v153
	s_and_b64 vcc, exec, s[44:45]
	global_store_dwordx2 v[162:163], v[164:165], off offset:288
	s_branch .LBB0_840
	v_add_co_u32_e32 v130, vcc, 0x28000, v150
	s_nop 1
	v_addc_co_u32_e32 v131, vcc, 0, v151, vcc
	v_add_co_u32_e32 v134, vcc, 0x2a000, v150
	s_nop 1
	v_addc_co_u32_e32 v135, vcc, 0, v151, vcc
	v_add_co_u32_e32 v138, vcc, 0x38000, v150
	global_load_dwordx4 v[130:133], v[130:131], off
	s_nop 0
	global_load_dwordx4 v[134:137], v[134:135], off
	v_addc_co_u32_e32 v139, vcc, 0, v151, vcc
	v_add_co_u32_e32 v142, vcc, 0x3a000, v150
	s_nop 1
	v_addc_co_u32_e32 v143, vcc, 0, v151, vcc
	global_load_dwordx4 v[138:141], v[138:139], off
	s_nop 0
	global_load_dwordx4 v[142:145], v[142:143], off
.LBB0_840:
	v_add_u32_e32 v162, 0xa0, v152
	v_ashrrev_i32_e32 v163, 31, v162
	v_lshlrev_b64 v[162:163], 11, v[162:163]
	v_lshl_add_u64 v[162:163], s[6:7], 0, v[162:163]
	v_add_f32_e32 v164, v48, v132
	v_add_f32_e32 v165, v49, v133
	v_add_f32_e32 v166, v46, v130
	v_add_f32_e32 v167, v47, v131
	v_lshl_add_u64 v[162:163], v[162:163], 0, s[86:87]
	v_cndmask_b32_e64 v153, v49, v165, s[42:43]
	v_cndmask_b32_e64 v161, v48, v164, s[42:43]
	v_cndmask_b32_e64 v164, v47, v167, s[42:43]
	v_cndmask_b32_e64 v165, v46, v166, s[42:43]
	v_lshl_add_u64 v[162:163], v[162:163], 0, v[0:1]
	v_cvt_pk_bf16_f32 v164, v165, v164
	v_cvt_pk_bf16_f32 v165, v161, v153
	global_store_dwordx2 v[162:163], v[164:165], off
	v_add_f32_e32 v164, v44, v136
	v_add_f32_e32 v165, v45, v137
	v_add_f32_e32 v166, v42, v134
	v_add_f32_e32 v167, v43, v135
	v_cndmask_b32_e64 v153, v45, v165, s[42:43]
	v_cndmask_b32_e64 v161, v44, v164, s[42:43]
	v_cndmask_b32_e64 v164, v43, v167, s[42:43]
	v_cndmask_b32_e64 v165, v42, v166, s[42:43]
	v_cvt_pk_bf16_f32 v164, v165, v164
	v_cvt_pk_bf16_f32 v165, v161, v153
	global_store_dwordx2 v[162:163], v[164:165], off offset:32
	v_add_f32_e32 v164, v16, v140
	v_add_f32_e32 v165, v17, v141
	v_add_f32_e32 v166, v14, v138
	v_add_f32_e32 v167, v15, v139
	v_cndmask_b32_e64 v153, v17, v165, s[42:43]
	v_cndmask_b32_e64 v161, v16, v164, s[42:43]
	v_cndmask_b32_e64 v164, v15, v167, s[42:43]
	v_cndmask_b32_e64 v165, v14, v166, s[42:43]
	v_cvt_pk_bf16_f32 v164, v165, v164
	v_cvt_pk_bf16_f32 v165, v161, v153
	global_store_dwordx2 v[162:163], v[164:165], off offset:256
	v_add_f32_e32 v164, v12, v144
	v_add_f32_e32 v165, v13, v145
	v_add_f32_e32 v166, v10, v142
	v_add_f32_e32 v167, v11, v143
	v_cndmask_b32_e64 v153, v13, v165, s[42:43]
	v_cndmask_b32_e64 v161, v12, v164, s[42:43]
	v_cndmask_b32_e64 v164, v11, v167, s[42:43]
	v_cndmask_b32_e64 v165, v10, v166, s[42:43]
	v_cvt_pk_bf16_f32 v164, v165, v164
	v_cvt_pk_bf16_f32 v165, v161, v153
	s_and_b64 vcc, exec, s[44:45]
	global_store_dwordx2 v[162:163], v[164:165], off offset:288
	s_branch .LBB0_842
	v_add_co_u32_e32 v130, vcc, 0x2c000, v150
	s_nop 1
	v_addc_co_u32_e32 v131, vcc, 0, v151, vcc
	v_add_co_u32_e32 v134, vcc, 0x2e000, v150
	s_nop 1
	v_addc_co_u32_e32 v135, vcc, 0, v151, vcc
	v_add_co_u32_e32 v138, vcc, 0x3c000, v150
	global_load_dwordx4 v[130:133], v[130:131], off
	s_nop 0
	global_load_dwordx4 v[134:137], v[134:135], off
	v_addc_co_u32_e32 v139, vcc, 0, v151, vcc
	v_add_co_u32_e32 v142, vcc, 0x3e000, v150
	s_nop 1
	v_addc_co_u32_e32 v143, vcc, 0, v151, vcc
	global_load_dwordx4 v[138:141], v[138:139], off
	s_nop 0
	global_load_dwordx4 v[142:145], v[142:143], off
.LBB0_842:
	v_add_u32_e32 v150, 0xb0, v152
	v_ashrrev_i32_e32 v151, 31, v150
	v_lshlrev_b64 v[150:151], 11, v[150:151]
	v_lshl_add_u64 v[150:151], s[6:7], 0, v[150:151]
	v_lshl_add_u64 v[150:151], v[150:151], 0, s[86:87]
	v_add_f32_e32 v132, v40, v132
	v_add_f32_e32 v133, v41, v133
	v_add_f32_e32 v130, v38, v130
	v_add_f32_e32 v131, v39, v131
	v_lshl_add_u64 v[150:151], v[150:151], 0, v[0:1]
	v_cndmask_b32_e64 v0, v41, v133, s[42:43]
	v_cndmask_b32_e64 v132, v40, v132, s[42:43]
	v_cndmask_b32_e64 v131, v39, v131, s[42:43]
	v_cndmask_b32_e64 v130, v38, v130, s[42:43]
	v_cvt_pk_bf16_f32 v130, v130, v131
	v_cvt_pk_bf16_f32 v131, v132, v0
	global_store_dwordx2 v[150:151], v[130:131], off
	v_add_f32_e32 v130, v36, v136
	v_add_f32_e32 v131, v37, v137
	v_add_f32_e32 v132, v34, v134
	v_add_f32_e32 v133, v35, v135
	v_cndmask_b32_e64 v0, v37, v131, s[42:43]
	v_cndmask_b32_e64 v131, v36, v130, s[42:43]
	v_cndmask_b32_e64 v130, v35, v133, s[42:43]
	v_cndmask_b32_e64 v132, v34, v132, s[42:43]
	v_cvt_pk_bf16_f32 v130, v132, v130
	v_cvt_pk_bf16_f32 v131, v131, v0
	global_store_dwordx2 v[150:151], v[130:131], off offset:32
	v_add_f32_e32 v130, v8, v140
	v_add_f32_e32 v131, v9, v141
	v_add_f32_e32 v132, v6, v138
	v_add_f32_e32 v133, v7, v139
	v_cndmask_b32_e64 v0, v9, v131, s[42:43]
	v_cndmask_b32_e64 v131, v8, v130, s[42:43]
	v_cndmask_b32_e64 v130, v7, v133, s[42:43]
	v_cndmask_b32_e64 v132, v6, v132, s[42:43]
	v_cvt_pk_bf16_f32 v130, v132, v130
	v_cvt_pk_bf16_f32 v131, v131, v0
	global_store_dwordx2 v[150:151], v[130:131], off offset:256
	v_add_f32_e32 v130, v4, v144
	v_add_f32_e32 v131, v5, v145
	v_add_f32_e32 v132, v2, v142
	v_add_f32_e32 v133, v3, v143
	v_cndmask_b32_e64 v0, v5, v131, s[42:43]
	v_cndmask_b32_e64 v131, v4, v130, s[42:43]
	v_cndmask_b32_e64 v130, v3, v133, s[42:43]
	v_cndmask_b32_e64 v132, v2, v132, s[42:43]
	v_cvt_pk_bf16_f32 v130, v132, v130
	v_cvt_pk_bf16_f32 v131, v131, v0
	s_mov_b64 s[16:17], 0
	global_store_dwordx2 v[150:151], v[130:131], off offset:288

.LBB0_849:
	s_cmpk_gt_i32 s5, 0xbf
	s_cselect_b32 s18, 0x80, 0
	v_readlane_b32 s0, v254, 1
	s_cmp_ge_i32 s0, s18
	s_movk_i32 s29, 0xfff
	s_mov_b32 s36, s65
	s_mov_b32 s65, s71
	s_mov_b32 s37, s73
	v_readlane_b32 s1, v254, 2
	s_cbranch_scc0 .LBB0_876
	v_readlane_b32 s0, v254, 1
	s_sub_i32 s0, s0, s18
	v_readlane_b32 s1, v254, 2
	v_lshl_add_u32 v52, s0, 9, v200
	s_mov_b32 s0, 0x3c0000
	v_cmp_gt_i32_e32 vcc, s0, v52
	s_and_saveexec_b64 s[2:3], vcc
	s_cbranch_execz .LBB0_875
	s_load_dwordx4 s[40:43], s[76:77], 0x70
	v_readlane_b32 s0, v254, 1
	s_sub_i32 s0, s0, s18
	s_lshl_b32 s0, s0, 9
	s_add_u32 s6, s12, 0xdc00000
	s_addc_u32 s7, s13, 0
	s_add_u32 s14, s12, 0xbe00000
	s_addc_u32 s15, s13, 0
	s_mul_i32 s8, s37, 0x2400
	s_mul_i32 s10, s37, 0xc00
	v_add_u32_e32 v91, s0, v200
	v_add_u32_e32 v92, 0x10000, v91
	v_add_u32_e32 v93, 0x20000, v91
	s_mov_b32 s1, 0xaaaaaaab
	v_mul_hi_u32 v88, v91, s1
	v_lshrrev_b32_e32 v88, 7, v88
	v_mul_u32_u24_e32 v2, 0xc0, v88
	v_sub_u32_e32 v2, v91, v2
	v_mul_hi_u32 v89, v92, s1
	v_lshrrev_b32_e32 v89, 7, v89
	v_mul_u32_u24_e32 v3, 0xc0, v89
	v_sub_u32_e32 v3, v92, v3
	v_mul_hi_u32 v90, v93, s1
	v_lshrrev_b32_e32 v90, 7, v90
	v_mul_u32_u24_e32 v4, 0xc0, v90
	v_sub_u32_e32 v4, v93, v4
	s_waitcnt lgkmcnt(0)
	s_add_u32 s16, s40, s8
	s_addc_u32 s17, s41, 0
	s_add_u32 s34, s16, 0x1800
	s_addc_u32 s35, s17, 0
	s_add_u32 s20, s42, s10
	s_addc_u32 s21, s43, 0
	v_lshlrev_b32_e32 v5, 4, v2
	global_load_dwordx4 v[100:103], v5, s[16:17]
	global_load_dwordx4 v[104:107], v5, s[16:17] offset:3072
	global_load_dwordx4 v[108:111], v5, s[34:35]
	global_load_dwordx4 v[112:115], v5, s[20:21]
	v_lshlrev_b32_e32 v6, 4, v3
	global_load_dwordx4 v[116:119], v6, s[16:17]
	global_load_dwordx4 v[120:123], v6, s[16:17] offset:3072
	global_load_dwordx4 v[124:127], v6, s[34:35]
	global_load_dwordx4 v[128:131], v6, s[20:21]
	v_lshlrev_b32_e32 v7, 4, v4
	global_load_dwordx4 v[132:135], v7, s[16:17]
	global_load_dwordx4 v[136:139], v7, s[16:17] offset:3072
	global_load_dwordx4 v[140:143], v7, s[34:35]
	global_load_dwordx4 v[144:147], v7, s[20:21]
	v_mov_b32_e32 v9, 0
	v_lshlrev_b32_e32 v8, 3, v91
	v_lshl_add_u64 v[70:71], s[14:15], 0, v[8:9]
	v_lshl_add_u64 v[76:77], s[6:7], 0, v[8:9]
	v_lshlrev_b32_e32 v8, 11, v88
	v_lshl_add_u32 v8, v2, 3, v8
	v_lshl_add_u64 v[82:83], s[22:23], 0, v[8:9]
	v_mov_b32_e32 v9, 0
	v_lshlrev_b32_e32 v8, 3, v92
	v_lshl_add_u64 v[72:73], s[14:15], 0, v[8:9]
	v_lshl_add_u64 v[78:79], s[6:7], 0, v[8:9]
	v_lshlrev_b32_e32 v8, 11, v89
	v_lshl_add_u32 v8, v3, 3, v8
	v_lshl_add_u64 v[84:85], s[22:23], 0, v[8:9]
	v_mov_b32_e32 v9, 0
	v_lshlrev_b32_e32 v8, 3, v93
	v_lshl_add_u64 v[74:75], s[14:15], 0, v[8:9]
	v_lshl_add_u64 v[80:81], s[6:7], 0, v[8:9]
	v_lshlrev_b32_e32 v8, 11, v90
	v_lshl_add_u32 v8, v4, 3, v8
	v_lshl_add_u64 v[86:87], s[22:23], 0, v[8:9]
	s_mov_b32 s0, 0x180000
	s_mov_b32 s1, 0
	s_mov_b32 s10, 0x200000
	s_mov_b32 s11, 0
	s_movk_i32 s4, 0xff
	s_mov_b32 s8, 0
	global_load_dwordx2 v[20:21], v[70:71], off
	global_load_dwordx2 v[22:23], v[70:71], off offset:-1536
	global_load_dwordx2 v[24:25], v[70:71], off offset:1536
	global_load_dwordx2 v[26:27], v[76:77], off
	global_load_dwordx2 v[28:29], v[72:73], off
	global_load_dwordx2 v[30:31], v[72:73], off offset:-1536
	global_load_dwordx2 v[32:33], v[72:73], off offset:1536
	global_load_dwordx2 v[34:35], v[78:79], off
	global_load_dwordx2 v[36:37], v[74:75], off
	global_load_dwordx2 v[38:39], v[74:75], off offset:-1536
	global_load_dwordx2 v[40:41], v[74:75], off offset:1536
	global_load_dwordx2 v[42:43], v[80:81], off
	v_lshl_add_u64 v[70:71], v[70:71], 0, s[0:1]
	v_lshl_add_u64 v[76:77], v[76:77], 0, s[0:1]
	v_lshl_add_u64 v[72:73], v[72:73], 0, s[0:1]
	v_lshl_add_u64 v[78:79], v[78:79], 0, s[0:1]
	v_lshl_add_u64 v[74:75], v[74:75], 0, s[0:1]
	v_lshl_add_u64 v[80:81], v[80:81], 0, s[0:1]
.Lconv_loop:
	global_load_dwordx2 v[44:45], v[70:71], off
	global_load_dwordx2 v[46:47], v[70:71], off offset:-1536
	global_load_dwordx2 v[48:49], v[70:71], off offset:1536
	global_load_dwordx2 v[50:51], v[76:77], off
	global_load_dwordx2 v[52:53], v[72:73], off
	global_load_dwordx2 v[54:55], v[72:73], off offset:-1536
	global_load_dwordx2 v[56:57], v[72:73], off offset:1536
	global_load_dwordx2 v[58:59], v[78:79], off
	global_load_dwordx2 v[60:61], v[74:75], off
	global_load_dwordx2 v[62:63], v[74:75], off offset:-1536
	global_load_dwordx2 v[64:65], v[74:75], off offset:1536
	global_load_dwordx2 v[66:67], v[80:81], off
	v_lshl_add_u64 v[70:71], v[70:71], 0, s[0:1]
	v_lshl_add_u64 v[76:77], v[76:77], 0, s[0:1]
	v_lshl_add_u64 v[72:73], v[72:73], 0, s[0:1]
	v_lshl_add_u64 v[78:79], v[78:79], 0, s[0:1]
	v_lshl_add_u64 v[74:75], v[74:75], 0, s[0:1]
	v_lshl_add_u64 v[80:81], v[80:81], 0, s[0:1]
	s_waitcnt vmcnt(12)
	v_and_b32_e32 v2, s4, v88
	v_cmp_ne_u32_e32 vcc, 0, v2
	v_lshlrev_b32_e32 v4, 16, v20
	v_and_b32_e32 v5, 0xffff0000, v20
	v_cndmask_b32_e32 v22, 0, v22, vcc
	v_cndmask_b32_e32 v23, 0, v23, vcc
	v_cmp_ne_u32_e32 vcc, s4, v2
	v_lshlrev_b32_e32 v6, 16, v21
	v_and_b32_e32 v7, 0xffff0000, v21
	v_cndmask_b32_e32 v24, 0, v24, vcc
	v_cndmask_b32_e32 v25, 0, v25, vcc
	v_lshlrev_b32_e32 v8, 16, v22
	v_and_b32_e32 v9, 0xffff0000, v22
	v_lshlrev_b32_e32 v10, 16, v23
	v_and_b32_e32 v11, 0xffff0000, v23
	v_lshlrev_b32_e32 v12, 16, v24
	v_and_b32_e32 v13, 0xffff0000, v24
	v_lshlrev_b32_e32 v14, 16, v25
	v_and_b32_e32 v15, 0xffff0000, v25
	v_lshlrev_b32_e32 v16, 16, v26
	v_and_b32_e32 v17, 0xffff0000, v26
	v_lshlrev_b32_e32 v18, 16, v27
	v_and_b32_e32 v19, 0xffff0000, v27
	v_fma_f32 v8, v100, v8, v112
	v_fma_f32 v9, v101, v9, v113
	v_fma_f32 v10, v102, v10, v114
	v_fma_f32 v11, v103, v11, v115
	v_fma_f32 v8, v104, v4, v8
	v_fma_f32 v9, v105, v5, v9
	v_fma_f32 v10, v106, v6, v10
	v_fma_f32 v11, v107, v7, v11
	v_fma_f32 v8, v108, v12, v8
	v_fma_f32 v9, v109, v13, v9
	v_fma_f32 v10, v110, v14, v10
	v_fma_f32 v11, v111, v15, v11
	v_mul_f32_e32 v8, v8, v16
	v_mul_f32_e32 v9, v9, v17
	v_mul_f32_e32 v10, v10, v18
	v_mul_f32_e32 v11, v11, v19
	v_cvt_pk_bf16_f32 v20, v8, v9
	v_cvt_pk_bf16_f32 v21, v10, v11
	global_store_dwordx2 v[82:83], v[20:21], off
	v_lshl_add_u64 v[82:83], v[82:83], 0, s[10:11]
	v_add_u32_e32 v88, 0x400, v88
	v_and_b32_e32 v2, s4, v89
	v_cmp_ne_u32_e32 vcc, 0, v2
	v_lshlrev_b32_e32 v4, 16, v28
	v_and_b32_e32 v5, 0xffff0000, v28
	v_cndmask_b32_e32 v30, 0, v30, vcc
	v_cndmask_b32_e32 v31, 0, v31, vcc
	v_cmp_ne_u32_e32 vcc, s4, v2
	v_lshlrev_b32_e32 v6, 16, v29
	v_and_b32_e32 v7, 0xffff0000, v29
	v_cndmask_b32_e32 v32, 0, v32, vcc
	v_cndmask_b32_e32 v33, 0, v33, vcc
	v_lshlrev_b32_e32 v8, 16, v30
	v_and_b32_e32 v9, 0xffff0000, v30
	v_lshlrev_b32_e32 v10, 16, v31
	v_and_b32_e32 v11, 0xffff0000, v31
	v_lshlrev_b32_e32 v12, 16, v32
	v_and_b32_e32 v13, 0xffff0000, v32
	v_lshlrev_b32_e32 v14, 16, v33
	v_and_b32_e32 v15, 0xffff0000, v33
	v_lshlrev_b32_e32 v16, 16, v34
	v_and_b32_e32 v17, 0xffff0000, v34
	v_lshlrev_b32_e32 v18, 16, v35
	v_and_b32_e32 v19, 0xffff0000, v35
	v_fma_f32 v8, v116, v8, v128
	v_fma_f32 v9, v117, v9, v129
	v_fma_f32 v10, v118, v10, v130
	v_fma_f32 v11, v119, v11, v131
	v_fma_f32 v8, v120, v4, v8
	v_fma_f32 v9, v121, v5, v9
	v_fma_f32 v10, v122, v6, v10
	v_fma_f32 v11, v123, v7, v11
	v_fma_f32 v8, v124, v12, v8
	v_fma_f32 v9, v125, v13, v9
	v_fma_f32 v10, v126, v14, v10
	v_fma_f32 v11, v127, v15, v11
	v_mul_f32_e32 v8, v8, v16
	v_mul_f32_e32 v9, v9, v17
	v_mul_f32_e32 v10, v10, v18
	v_mul_f32_e32 v11, v11, v19
	v_cvt_pk_bf16_f32 v28, v8, v9
	v_cvt_pk_bf16_f32 v29, v10, v11
	global_store_dwordx2 v[84:85], v[28:29], off
	v_lshl_add_u64 v[84:85], v[84:85], 0, s[10:11]
	v_add_u32_e32 v89, 0x400, v89
	v_and_b32_e32 v2, s4, v90
	v_cmp_ne_u32_e32 vcc, 0, v2
	v_lshlrev_b32_e32 v4, 16, v36
	v_and_b32_e32 v5, 0xffff0000, v36
	v_cndmask_b32_e32 v38, 0, v38, vcc
	v_cndmask_b32_e32 v39, 0, v39, vcc
	v_cmp_ne_u32_e32 vcc, s4, v2
	v_lshlrev_b32_e32 v6, 16, v37
	v_and_b32_e32 v7, 0xffff0000, v37
	v_cndmask_b32_e32 v40, 0, v40, vcc
	v_cndmask_b32_e32 v41, 0, v41, vcc
	v_lshlrev_b32_e32 v8, 16, v38
	v_and_b32_e32 v9, 0xffff0000, v38
	v_lshlrev_b32_e32 v10, 16, v39
	v_and_b32_e32 v11, 0xffff0000, v39
	v_lshlrev_b32_e32 v12, 16, v40
	v_and_b32_e32 v13, 0xffff0000, v40
	v_lshlrev_b32_e32 v14, 16, v41
	v_and_b32_e32 v15, 0xffff0000, v41
	v_lshlrev_b32_e32 v16, 16, v42
	v_and_b32_e32 v17, 0xffff0000, v42
	v_lshlrev_b32_e32 v18, 16, v43
	v_and_b32_e32 v19, 0xffff0000, v43
	v_fma_f32 v8, v132, v8, v144
	v_fma_f32 v9, v133, v9, v145
	v_fma_f32 v10, v134, v10, v146
	v_fma_f32 v11, v135, v11, v147
	v_fma_f32 v8, v136, v4, v8
	v_fma_f32 v9, v137, v5, v9
	v_fma_f32 v10, v138, v6, v10
	v_fma_f32 v11, v139, v7, v11
	v_fma_f32 v8, v140, v12, v8
	v_fma_f32 v9, v141, v13, v9
	v_fma_f32 v10, v142, v14, v10
	v_fma_f32 v11, v143, v15, v11
	v_mul_f32_e32 v8, v8, v16
	v_mul_f32_e32 v9, v9, v17
	v_mul_f32_e32 v10, v10, v18
	v_mul_f32_e32 v11, v11, v19
	v_cvt_pk_bf16_f32 v36, v8, v9
	v_cvt_pk_bf16_f32 v37, v10, v11
	global_store_dwordx2 v[86:87], v[36:37], off
	v_lshl_add_u64 v[86:87], v[86:87], 0, s[10:11]
	v_add_u32_e32 v90, 0x400, v90
	global_load_dwordx2 v[20:21], v[70:71], off
	global_load_dwordx2 v[22:23], v[70:71], off offset:-1536
	global_load_dwordx2 v[24:25], v[70:71], off offset:1536
	global_load_dwordx2 v[26:27], v[76:77], off
	global_load_dwordx2 v[28:29], v[72:73], off
	global_load_dwordx2 v[30:31], v[72:73], off offset:-1536
	global_load_dwordx2 v[32:33], v[72:73], off offset:1536
	global_load_dwordx2 v[34:35], v[78:79], off
	global_load_dwordx2 v[36:37], v[74:75], off
	global_load_dwordx2 v[38:39], v[74:75], off offset:-1536
	global_load_dwordx2 v[40:41], v[74:75], off offset:1536
	global_load_dwordx2 v[42:43], v[80:81], off
	v_lshl_add_u64 v[70:71], v[70:71], 0, s[0:1]
	v_lshl_add_u64 v[76:77], v[76:77], 0, s[0:1]
	v_lshl_add_u64 v[72:73], v[72:73], 0, s[0:1]
	v_lshl_add_u64 v[78:79], v[78:79], 0, s[0:1]
	v_lshl_add_u64 v[74:75], v[74:75], 0, s[0:1]
	v_lshl_add_u64 v[80:81], v[80:81], 0, s[0:1]
	s_waitcnt vmcnt(12)
	v_and_b32_e32 v2, s4, v88
	v_cmp_ne_u32_e32 vcc, 0, v2
	v_lshlrev_b32_e32 v4, 16, v44
	v_and_b32_e32 v5, 0xffff0000, v44
	v_cndmask_b32_e32 v46, 0, v46, vcc
	v_cndmask_b32_e32 v47, 0, v47, vcc
	v_cmp_ne_u32_e32 vcc, s4, v2
	v_lshlrev_b32_e32 v6, 16, v45
	v_and_b32_e32 v7, 0xffff0000, v45
	v_cndmask_b32_e32 v48, 0, v48, vcc
	v_cndmask_b32_e32 v49, 0, v49, vcc
	v_lshlrev_b32_e32 v8, 16, v46
	v_and_b32_e32 v9, 0xffff0000, v46
	v_lshlrev_b32_e32 v10, 16, v47
	v_and_b32_e32 v11, 0xffff0000, v47
	v_lshlrev_b32_e32 v12, 16, v48
	v_and_b32_e32 v13, 0xffff0000, v48
	v_lshlrev_b32_e32 v14, 16, v49
	v_and_b32_e32 v15, 0xffff0000, v49
	v_lshlrev_b32_e32 v16, 16, v50
	v_and_b32_e32 v17, 0xffff0000, v50
	v_lshlrev_b32_e32 v18, 16, v51
	v_and_b32_e32 v19, 0xffff0000, v51
	v_fma_f32 v8, v100, v8, v112
	v_fma_f32 v9, v101, v9, v113
	v_fma_f32 v10, v102, v10, v114
	v_fma_f32 v11, v103, v11, v115
	v_fma_f32 v8, v104, v4, v8
	v_fma_f32 v9, v105, v5, v9
	v_fma_f32 v10, v106, v6, v10
	v_fma_f32 v11, v107, v7, v11
	v_fma_f32 v8, v108, v12, v8
	v_fma_f32 v9, v109, v13, v9
	v_fma_f32 v10, v110, v14, v10
	v_fma_f32 v11, v111, v15, v11
	v_mul_f32_e32 v8, v8, v16
	v_mul_f32_e32 v9, v9, v17
	v_mul_f32_e32 v10, v10, v18
	v_mul_f32_e32 v11, v11, v19
	v_cvt_pk_bf16_f32 v44, v8, v9
	v_cvt_pk_bf16_f32 v45, v10, v11
	global_store_dwordx2 v[82:83], v[44:45], off
	v_lshl_add_u64 v[82:83], v[82:83], 0, s[10:11]
	v_add_u32_e32 v88, 0x400, v88
	v_and_b32_e32 v2, s4, v89
	v_cmp_ne_u32_e32 vcc, 0, v2
	v_lshlrev_b32_e32 v4, 16, v52
	v_and_b32_e32 v5, 0xffff0000, v52
	v_cndmask_b32_e32 v54, 0, v54, vcc
	v_cndmask_b32_e32 v55, 0, v55, vcc
	v_cmp_ne_u32_e32 vcc, s4, v2
	v_lshlrev_b32_e32 v6, 16, v53
	v_and_b32_e32 v7, 0xffff0000, v53
	v_cndmask_b32_e32 v56, 0, v56, vcc
	v_cndmask_b32_e32 v57, 0, v57, vcc
	v_lshlrev_b32_e32 v8, 16, v54
	v_and_b32_e32 v9, 0xffff0000, v54
	v_lshlrev_b32_e32 v10, 16, v55
	v_and_b32_e32 v11, 0xffff0000, v55
	v_lshlrev_b32_e32 v12, 16, v56
	v_and_b32_e32 v13, 0xffff0000, v56
	v_lshlrev_b32_e32 v14, 16, v57
	v_and_b32_e32 v15, 0xffff0000, v57
	v_lshlrev_b32_e32 v16, 16, v58
	v_and_b32_e32 v17, 0xffff0000, v58
	v_lshlrev_b32_e32 v18, 16, v59
	v_and_b32_e32 v19, 0xffff0000, v59
	v_fma_f32 v8, v116, v8, v128
	v_fma_f32 v9, v117, v9, v129
	v_fma_f32 v10, v118, v10, v130
	v_fma_f32 v11, v119, v11, v131
	v_fma_f32 v8, v120, v4, v8
	v_fma_f32 v9, v121, v5, v9
	v_fma_f32 v10, v122, v6, v10
	v_fma_f32 v11, v123, v7, v11
	v_fma_f32 v8, v124, v12, v8
	v_fma_f32 v9, v125, v13, v9
	v_fma_f32 v10, v126, v14, v10
	v_fma_f32 v11, v127, v15, v11
	v_mul_f32_e32 v8, v8, v16
	v_mul_f32_e32 v9, v9, v17
	v_mul_f32_e32 v10, v10, v18
	v_mul_f32_e32 v11, v11, v19
	v_cvt_pk_bf16_f32 v52, v8, v9
	v_cvt_pk_bf16_f32 v53, v10, v11
	global_store_dwordx2 v[84:85], v[52:53], off
	v_lshl_add_u64 v[84:85], v[84:85], 0, s[10:11]
	v_add_u32_e32 v89, 0x400, v89
	v_and_b32_e32 v2, s4, v90
	v_cmp_ne_u32_e32 vcc, 0, v2
	v_lshlrev_b32_e32 v4, 16, v60
	v_and_b32_e32 v5, 0xffff0000, v60
	v_cndmask_b32_e32 v62, 0, v62, vcc
	v_cndmask_b32_e32 v63, 0, v63, vcc
	v_cmp_ne_u32_e32 vcc, s4, v2
	v_lshlrev_b32_e32 v6, 16, v61
	v_and_b32_e32 v7, 0xffff0000, v61
	v_cndmask_b32_e32 v64, 0, v64, vcc
	v_cndmask_b32_e32 v65, 0, v65, vcc
	v_lshlrev_b32_e32 v8, 16, v62
	v_and_b32_e32 v9, 0xffff0000, v62
	v_lshlrev_b32_e32 v10, 16, v63
	v_and_b32_e32 v11, 0xffff0000, v63
	v_lshlrev_b32_e32 v12, 16, v64
	v_and_b32_e32 v13, 0xffff0000, v64
	v_lshlrev_b32_e32 v14, 16, v65
	v_and_b32_e32 v15, 0xffff0000, v65
	v_lshlrev_b32_e32 v16, 16, v66
	v_and_b32_e32 v17, 0xffff0000, v66
	v_lshlrev_b32_e32 v18, 16, v67
	v_and_b32_e32 v19, 0xffff0000, v67
	v_fma_f32 v8, v132, v8, v144
	v_fma_f32 v9, v133, v9, v145
	v_fma_f32 v10, v134, v10, v146
	v_fma_f32 v11, v135, v11, v147
	v_fma_f32 v8, v136, v4, v8
	v_fma_f32 v9, v137, v5, v9
	v_fma_f32 v10, v138, v6, v10
	v_fma_f32 v11, v139, v7, v11
	v_fma_f32 v8, v140, v12, v8
	v_fma_f32 v9, v141, v13, v9
	v_fma_f32 v10, v142, v14, v10
	v_fma_f32 v11, v143, v15, v11
	v_mul_f32_e32 v8, v8, v16
	v_mul_f32_e32 v9, v9, v17
	v_mul_f32_e32 v10, v10, v18
	v_mul_f32_e32 v11, v11, v19
	v_cvt_pk_bf16_f32 v60, v8, v9
	v_cvt_pk_bf16_f32 v61, v10, v11
	global_store_dwordx2 v[86:87], v[60:61], off
	v_lshl_add_u64 v[86:87], v[86:87], 0, s[10:11]
	v_add_u32_e32 v90, 0x400, v90
	s_add_i32 s8, s8, 1
	s_cmp_eq_u32 s8, 2
	s_cselect_b32 s4, 0x7ff, s4
	s_cmp_lt_u32 s8, 10
	s_cbranch_scc1 .Lconv_loop
	s_waitcnt vmcnt(0)
